# retention intra-chunk decay mask: exponent argument formed by one fma per element off a shared base (the 1/16 scale folded in as -4 in the exponent), compares against the shared index; about 35 fewer
# speedup vs baseline: 1.0140x; 1.0061x over previous
.LBB0_123:
	s_nop 3
	v_add_u32_e32 v124, 0x11000, v249
	v_add_u32_e32 v126, 0x11a00, v249
	v_add_u32_e32 v128, 0x11020, v249
	v_add_u32_e32 v130, 0x11a20, v249
	v_add_u32_e32 v132, 0x11040, v249
	v_add_u32_e32 v134, 0x11a40, v249
	v_add_u32_e32 v136, 0x11060, v249
	v_add_u32_e32 v138, 0x11a60, v249
	ds_read_b64_tr_b16 v[124:125], v124
	ds_read_b64_tr_b16 v[126:127], v126
	ds_read_b64_tr_b16 v[128:129], v128
	ds_read_b64_tr_b16 v[130:131], v130
	ds_read_b64_tr_b16 v[132:133], v132
	ds_read_b64_tr_b16 v[134:135], v134
	ds_read_b64_tr_b16 v[136:137], v136
	ds_read_b64_tr_b16 v[138:139], v138
	v_add_u32_e32 v172, v187, v248
	v_cvt_f32_i32_e32 v173, v172
	s_add_i32 s54, s54, -1
	s_add_i32 s11, s11, 32
	v_fma_f32 v173, v155, v173, -4.0
	s_add_i32 s53, s53, 2
	v_add_u32_e32 v249, 0x1400, v249
	v_subrev_u32_e32 v248, 32, v248
	v_add_u32_e32 v161, 16, v161
	v_add_u32_e32 v157, 0x4400, v157
	s_cmp_eq_u32 s54, 0
	v_exp_f32_e32 v174, v173
	v_fmamk_f32 v175, v155, 0xbf800000, v173
	v_exp_f32_e32 v175, v175
	v_cmp_le_i32_e32 vcc, 0, v172
	v_cmp_le_i32_e64 s[100:101], 1, v172
	v_mul_f32_e32 v140, v174, v140
	v_mul_f32_e32 v141, v175, v141
	v_cndmask_b32_e32 v140, 0, v140, vcc
	v_cndmask_b32_e64 v141, 0, v141, s[100:101]
	v_fmamk_f32 v174, v155, 0xc0000000, v173
	v_exp_f32_e32 v174, v174
	v_fmamk_f32 v175, v155, 0xc0400000, v173
	v_exp_f32_e32 v175, v175
	v_cmp_le_i32_e32 vcc, 2, v172
	v_cmp_le_i32_e64 s[100:101], 3, v172
	v_mul_f32_e32 v142, v174, v142
	v_mul_f32_e32 v143, v175, v143
	v_cndmask_b32_e32 v142, 0, v142, vcc
	v_cndmask_b32_e64 v143, 0, v143, s[100:101]
	v_fmamk_f32 v174, v155, 0xc1800000, v173
	v_exp_f32_e32 v174, v174
	v_fmamk_f32 v175, v155, 0xc1880000, v173
	v_exp_f32_e32 v175, v175
	v_cmp_le_i32_e32 vcc, 16, v172
	v_cmp_le_i32_e64 s[100:101], 17, v172
	v_mul_f32_e32 v120, v174, v120
	v_mul_f32_e32 v121, v175, v121
	v_cndmask_b32_e32 v120, 0, v120, vcc
	v_cndmask_b32_e64 v121, 0, v121, s[100:101]
	v_fmamk_f32 v174, v155, 0xc1900000, v173
	v_exp_f32_e32 v174, v174
	v_fmamk_f32 v175, v155, 0xc1980000, v173
	v_exp_f32_e32 v175, v175
	v_cmp_le_i32_e32 vcc, 18, v172
	v_cmp_le_i32_e64 s[100:101], 19, v172
	v_mul_f32_e32 v122, v174, v122
	v_mul_f32_e32 v123, v175, v123
	v_cndmask_b32_e32 v122, 0, v122, vcc
	v_cndmask_b32_e64 v123, 0, v123, s[100:101]
	v_cvt_pk_bf16_f32 v174, v120, v121
	v_cvt_pk_bf16_f32 v123, v122, v123
	v_cvt_pk_bf16_f32 v120, v140, v141
	v_cvt_pk_bf16_f32 v121, v142, v143
	v_mov_b32_e32 v122, v174
	s_waitcnt lgkmcnt(6)
	s_nop 0
	v_mfma_f32_16x16x32_bf16 v[104:107], v[124:127], v[120:123], v[104:107]
	s_waitcnt lgkmcnt(4)
	v_mfma_f32_16x16x32_bf16 v[108:111], v[128:131], v[120:123], v[108:111]
	s_waitcnt lgkmcnt(2)
	v_mfma_f32_16x16x32_bf16 v[112:115], v[132:135], v[120:123], v[112:115]
	s_waitcnt lgkmcnt(0)
	v_mfma_f32_16x16x32_bf16 v[116:119], v[136:139], v[120:123], v[116:119]
	s_cbranch_scc1 .LBB0_128

	.amdhsa_kernel _Z4mega6Params
		.amdhsa_group_segment_fixed_size 151568
		.amdhsa_private_segment_fixed_size 0
		.amdhsa_kernarg_size 464
		.amdhsa_user_sgpr_count 2
		.amdhsa_user_sgpr_dispatch_ptr 0
		.amdhsa_user_sgpr_queue_ptr 0
		.amdhsa_user_sgpr_kernarg_segment_ptr 1
		.amdhsa_user_sgpr_dispatch_id 0
		.amdhsa_user_sgpr_kernarg_preload_length 0
		.amdhsa_user_sgpr_kernarg_preload_offset 0
		.amdhsa_user_sgpr_private_segment_size 0
		.amdhsa_uses_dynamic_stack 0
		.amdhsa_enable_private_segment 0
		.amdhsa_system_sgpr_workgroup_id_x 1
		.amdhsa_system_sgpr_workgroup_id_y 0
		.amdhsa_system_sgpr_workgroup_id_z 0
		.amdhsa_system_sgpr_workgroup_info 0
		.amdhsa_system_vgpr_workitem_id 2
		.amdhsa_next_free_vgpr 256
		.amdhsa_next_free_sgpr 102
		.amdhsa_accum_offset 256
		.amdhsa_reserve_vcc 1
		.amdhsa_float_round_mode_32 0
		.amdhsa_float_round_mode_16_64 0
		.amdhsa_float_denorm_mode_32 3
		.amdhsa_float_denorm_mode_16_64 3
		.amdhsa_dx10_clamp 1
		.amdhsa_ieee_mode 1
		.amdhsa_fp16_overflow 0
		.amdhsa_tg_split 0
		.amdhsa_exception_fp_ieee_invalid_op 0
		.amdhsa_exception_fp_denorm_src 0
		.amdhsa_exception_fp_ieee_div_zero 0
		.amdhsa_exception_fp_ieee_overflow 0
		.amdhsa_exception_fp_ieee_underflow 0
		.amdhsa_exception_fp_ieee_inexact 0
		.amdhsa_exception_int_div_zero 0
	.end_amdhsa_kernel

amdhsa.kernels:
  - .agpr_count:     0
    .args:
      - .offset:         0
        .size:           208
        .value_kind:     by_value
      - .offset:         208
        .size:           4
        .value_kind:     hidden_block_count_x
      - .offset:         212
        .size:           4
        .value_kind:     hidden_block_count_y
      - .offset:         216
        .size:           4
        .value_kind:     hidden_block_count_z
      - .offset:         220
        .size:           2
        .value_kind:     hidden_group_size_x
      - .offset:         222
        .size:           2
        .value_kind:     hidden_group_size_y
      - .offset:         224
        .size:           2
        .value_kind:     hidden_group_size_z
      - .offset:         226
        .size:           2
        .value_kind:     hidden_remainder_x
      - .offset:         228
        .size:           2
        .value_kind:     hidden_remainder_y
      - .offset:         230
        .size:           2
        .value_kind:     hidden_remainder_z
      - .offset:         248
        .size:           8
        .value_kind:     hidden_global_offset_x
      - .offset:         256
        .size:           8
        .value_kind:     hidden_global_offset_y
      - .offset:         264
        .size:           8
        .value_kind:     hidden_global_offset_z
      - .offset:         272
        .size:           2
        .value_kind:     hidden_grid_dims
      - .offset:         296
        .size:           8
        .value_kind:     hidden_multigrid_sync_arg
    .group_segment_fixed_size: 151568
    .kernarg_segment_align: 8
    .kernarg_segment_size: 464
    .language:       OpenCL C
    .language_version:
      - 2
      - 0
    .max_flat_workgroup_size: 512
    .name:           _Z4mega6Params
    .private_segment_fixed_size: 0
    .sgpr_count:     108
    .sgpr_spill_count: 268
    .symbol:         _Z4mega6Params.kd
    .uniform_work_group_size: 1
    .uses_dynamic_stack: false
    .vgpr_count:     256
    .vgpr_spill_count: 0
    .wavefront_size: 64
